# T10 for stick-breaking KV loop: V row-major ds_write_b128 + ds_read_b64_tr_b16, all 8 PV fragments prefetched into dead temporaries before the exp section tail
# speedup vs baseline: 1.0500x; 1.0010x over previous
; #define LAS __attribute__((address_space(3)))
; __device__ __forceinline__ float sum32(float v) { auto rr = __builtin_amdgcn_permlane32_swap(__float_as_uint(v), __float_as_uint(v), false, false); return __uint_as_float(rr[0]) + __uint_as_float(rr[1]); }
; #define UNPACK8(v, k) const float k##0 = blo(v.x), k##1 = bhi(v.x), k##2 = blo(v.y), k##3 = bhi(v.y), k##4 = blo(v.z), k##5 = bhi(v.z), k##6 = blo(v.w), k##7 = bhi(v.w)
; __device__ __forceinline__ unsigned cvtpk(float lo, float hi) { f32x2_t v = {lo, hi}; bf16x2_t b = __builtin_convertvector(v, bf16x2_t); return __builtin_bit_cast(unsigned, b); }
; template <bool NORM> __device__ __forceinline__ void kv_store(u32x4 kc, u32x4 vc, const float (&g)[8], LAS unsigned char* ksb, LAS unsigned char* vtb, int tid) {
;     ...
;     *(LAS u32x4*)(ksb + kl * KSB + ch * 16) = kc;
;     LAS unsigned short* vp = (LAS unsigned short*)(vtb + (8 * ch) * VTB + kl * 2);
;     vp[0 * (VTB / 2)] = (unsigned short)(vc.x & 0xffffu); vp[1 * (VTB / 2)] = (unsigned short)(vc.x >> 16);
;     vp[2 * (VTB / 2)] = (unsigned short)(vc.y & 0xffffu); vp[3 * (VTB / 2)] = (unsigned short)(vc.y >> 16);
;     vp[4 * (VTB / 2)] = (unsigned short)(vc.z & 0xffffu); vp[5 * (VTB / 2)] = (unsigned short)(vc.z >> 16);
;     vp[6 * (VTB / 2)] = (unsigned short)(vc.w & 0xffffu); vp[7 * (VTB / 2)] = (unsigned short)(vc.w >> 16);
; }
; template <bool NORM> __device__ __forceinline__ void load_qfrag(bf16x8 (&qf)[4], const bf16_t* qrow, const float* g1, const float* g2, float sc, int hh) {
;     ...
;     for (int s = 0; s < 4; ++s) { const u32x4 v = *(const u32x4*)(qrow + 16 * s + 8 * hh); UNPACK8(v, k);
;         f[8 * s] = k0; f[8 * s + 1] = k1; f[8 * s + 2] = k2; f[8 * s + 3] = k3; f[8 * s + 4] = k4; f[8 * s + 5] = k5; f[8 * s + 6] = k6; f[8 * s + 7] = k7; }
;     if (NORM) { float ss = 0.f;
; #pragma unroll
;         for (int i = 0; i < 32; ++i) ss += f[i] * f[i];
;         ss = sum32(ss); sc *= rsqrtf(ss * (1.f / 64.f) + EPS); }
; #pragma unroll
;     for (int s = 0; s < 4; ++s) { float v[8];
; #pragma unroll
;         for (int j = 0; j < 8; ++j) { const int d = 16 * s + 8 * hh + j; v[j] = f[8 * s + j] * sc * (g1 ? g1[d] : 1.f) * (g2 ? g2[d] : 1.f); }
;         u32x4 w; w.x = cvtpk(v[0], v[1]); w.y = cvtpk(v[2], v[3]); w.z = cvtpk(v[4], v[5]); w.w = cvtpk(v[6], v[7]);
;         qf[s] = __builtin_bit_cast(bf16x8, w); }
.LBB0_886:
	s_or_b64 exec, exec, s[4:5]
	s_waitcnt vmcnt(3)
	v_lshlrev_b32_e32 v22, 16, v14
	v_and_b32_e32 v23, 0xffff0000, v14
	s_mov_b32 s4, 0x3e38aa3b
	v_lshlrev_b32_e32 v14, 16, v15
	v_and_b32_e32 v15, 0xffff0000, v15
	v_pk_mul_f32 v[14:15], v[14:15], s[4:5] op_sel_hi:[1,0]
	v_lshlrev_b32_e32 v24, 16, v16
	v_and_b32_e32 v25, 0xffff0000, v16
	v_lshlrev_b32_e32 v16, 16, v17
	v_and_b32_e32 v17, 0xffff0000, v17
	v_pk_mul_f32 v[16:17], v[16:17], s[4:5] op_sel_hi:[1,0]
	v_cvt_pk_bf16_f32 v75, v14, v15
	s_waitcnt vmcnt(2)
	v_lshlrev_b32_e32 v14, 16, v10
	v_and_b32_e32 v15, 0xffff0000, v10
	v_lshlrev_b32_e32 v10, 16, v11
	v_and_b32_e32 v11, 0xffff0000, v11
	v_cvt_pk_bf16_f32 v77, v16, v17
	v_pk_mul_f32 v[10:11], v[10:11], s[4:5] op_sel_hi:[1,0]
	v_lshlrev_b32_e32 v16, 16, v12
	v_and_b32_e32 v17, 0xffff0000, v12
	v_lshlrev_b32_e32 v12, 16, v13
	v_and_b32_e32 v13, 0xffff0000, v13
	v_pk_mul_f32 v[12:13], v[12:13], s[4:5] op_sel_hi:[1,0]
	v_cvt_pk_bf16_f32 v79, v10, v11
	s_waitcnt vmcnt(1)
	v_lshlrev_b32_e32 v10, 16, v6
	v_and_b32_e32 v11, 0xffff0000, v6
	v_lshlrev_b32_e32 v6, 16, v7
	v_and_b32_e32 v7, 0xffff0000, v7
	v_cvt_pk_bf16_f32 v81, v12, v13
	v_pk_mul_f32 v[6:7], v[6:7], s[4:5] op_sel_hi:[1,0]
	v_lshlrev_b32_e32 v12, 16, v8
	v_and_b32_e32 v13, 0xffff0000, v8
	v_lshlrev_b32_e32 v8, 16, v9
	v_and_b32_e32 v9, 0xffff0000, v9
	v_pk_mul_f32 v[8:9], v[8:9], s[4:5] op_sel_hi:[1,0]
	v_cvt_pk_bf16_f32 v83, v6, v7
	s_waitcnt vmcnt(0)
	v_lshlrev_b32_e32 v6, 16, v2
	v_and_b32_e32 v7, 0xffff0000, v2
	v_lshlrev_b32_e32 v2, 16, v3
	v_and_b32_e32 v3, 0xffff0000, v3
	v_pk_mul_f32 v[14:15], v[14:15], s[4:5] op_sel_hi:[1,0]
	v_cvt_pk_bf16_f32 v85, v8, v9
	v_pk_mul_f32 v[2:3], v[2:3], s[4:5] op_sel_hi:[1,0]
	v_lshlrev_b32_e32 v8, 16, v4
	v_and_b32_e32 v9, 0xffff0000, v4
	v_lshlrev_b32_e32 v4, 16, v5
	v_and_b32_e32 v5, 0xffff0000, v5
	v_and_b32_e32 v21, 63, v20
	v_pk_mul_f32 v[22:23], v[22:23], s[4:5] op_sel_hi:[1,0]
	v_pk_mul_f32 v[24:25], v[24:25], s[4:5] op_sel_hi:[1,0]
	v_cvt_pk_bf16_f32 v78, v14, v15
	v_pk_mul_f32 v[10:11], v[10:11], s[4:5] op_sel_hi:[1,0]
	v_pk_mul_f32 v[12:13], v[12:13], s[4:5] op_sel_hi:[1,0]
	v_pk_mul_f32 v[6:7], v[6:7], s[4:5] op_sel_hi:[1,0]
	v_pk_mul_f32 v[8:9], v[8:9], s[4:5] op_sel_hi:[1,0]
	v_pk_mul_f32 v[4:5], v[4:5], s[4:5] op_sel_hi:[1,0]
	v_cvt_pk_bf16_f32 v87, v2, v3
	v_and_b32_e32 v2, 7, v20
	v_mov_b32_e32 v14, v1
	v_mov_b32_e32 v15, v1
	v_lshlrev_b32_e32 v117, 3, v19
	v_cvt_pk_bf16_f32 v74, v22, v23
	v_cvt_pk_bf16_f32 v76, v24, v25
	v_pk_mul_f32 v[16:17], v[16:17], s[4:5] op_sel_hi:[1,0]
	v_cvt_pk_bf16_f32 v82, v10, v11
	v_cvt_pk_bf16_f32 v84, v12, v13
	v_cvt_pk_bf16_f32 v86, v6, v7
	v_cvt_pk_bf16_f32 v88, v8, v9
	v_cvt_pk_bf16_f32 v89, v4, v5
	s_lshl_b32 s4, s7, 2
	v_lshlrev_b32_e32 v119, 4, v2
	v_lshlrev_b32_e32 v120, 4, v2
	v_lshl_add_u64 v[96:97], v[0:1], 1, s[0:1]
	v_mul_u32_u24_e32 v122, 0x90, v18
	v_lshlrev_b32_e32 v93, 2, v19
	v_cmp_gt_u32_e64 s[0:1], 32, v21
	v_bfe_u32 v117, v18, 2, 2
	v_lshl_add_u32 v117, v19, 2, v117
	v_mul_u32_u24_e32 v123, 0xc0, v117
	v_bfe_u32 v117, v18, 4, 1
	v_lshl_add_u32 v123, v117, 5, v123
	v_and_b32_e32 v117, 3, v18
	v_lshl_add_u32 v123, v117, 3, v123
	v_cmp_eq_u32_e64 s[40:41], 0, v21
	v_mov_b32_e32 v0, v1
	v_mov_b32_e32 v2, v1
	v_mov_b32_e32 v3, v1
	v_mov_b32_e32 v4, v1
	v_mov_b32_e32 v5, v1
	v_mov_b32_e32 v6, v1
	v_mov_b32_e32 v7, v1
	v_mov_b32_e32 v8, v1
	v_mov_b32_e32 v9, v1
	v_mov_b32_e32 v10, v1
	v_mov_b32_e32 v11, v1
	v_mov_b32_e32 v12, v1
	v_mov_b32_e32 v13, v1
	v_mov_b64_e32 v[32:33], v[14:15]
	v_cvt_pk_bf16_f32 v80, v16, v17
	s_add_i32 s13, s4, 0
	s_movk_i32 s4, 0x90
	v_mov_b64_e32 v[30:31], v[12:13]
	v_mov_b64_e32 v[28:29], v[10:11]
	v_mov_b64_e32 v[26:27], v[8:9]
	v_mov_b64_e32 v[24:25], v[6:7]
	v_mov_b64_e32 v[22:23], v[4:5]
	v_mov_b64_e32 v[20:21], v[2:3]
	v_mov_b64_e32 v[18:19], v[0:1]
	v_mov_b64_e32 v[16:17], v[14:15]
	v_ashrrev_i32_e32 v91, 31, v90
	v_mul_lo_u32 v118, v116, s4
	v_mul_u32_u24_e32 v121, 0xc0, v116
	v_add_u32_e32 v120, v120, v121
	s_or_b32 s24, s6, 30
	s_add_i32 s25, s8, 2
	s_mov_b64 s[4:5], 0
	v_mov_b64_e32 v[14:15], v[12:13]
	v_mov_b64_e32 v[12:13], v[10:11]
	v_mov_b64_e32 v[10:11], v[8:9]
	v_mov_b64_e32 v[8:9], v[6:7]
	v_mov_b64_e32 v[6:7], v[4:5]
	v_mov_b64_e32 v[4:5], v[2:3]
	v_mov_b64_e32 v[2:3], v[0:1]
.LBB0_887:
	s_mul_i32 s6, s12, 0x2400
	s_add_i32 s8, s6, 0
	s_lshl_b32 s6, s12, 9
	s_xor_b32 s36, s12, 1
	s_mul_i32 s37, s12, 0x3000
	v_add3_u32 v0, s8, v118, v119
	s_lshl_b32 s6, s36, 5
	s_waitcnt vmcnt(1)
	ds_write_b128 v0, v[70:73]
	v_add_u32_e32 v0, s37, v120
	s_add_i32 s6, s6, 0
	s_waitcnt vmcnt(0)
	ds_write_b128 v0, v[66:69] offset:36864
	v_mov_b32_e32 v0, s6
	s_waitcnt lgkmcnt(0)
	s_barrier
	ds_read_b128 v[34:37], v0 offset:35840
	ds_read_b128 v[38:41], v0 offset:35856
	s_cmp_eq_u32 s25, -1
	s_cselect_b64 s[6:7], -1, 0
	s_waitcnt lgkmcnt(1)
	v_and_b32_e32 v0, v35, v34
	v_and_b32_e32 v0, v0, v36
	v_and_b32_e32 v0, v0, v37
	s_waitcnt lgkmcnt(0)
	v_and_b32_e32 v0, v0, v38
	v_and_b32_e32 v0, v0, v39
	v_and_b32_e32 v0, v0, v40
	v_and_b32_e32 v0, v0, v41
	v_cmp_ne_u32_e32 vcc, 0, v0
	s_or_b64 s[6:7], s[6:7], vcc
	s_and_b64 s[6:7], s[6:7], exec
	s_cselect_b32 s6, -1, s25
	s_cmp_lt_i32 s6, 0
	s_cselect_b64 s[26:27], -1, 0
	s_and_b64 vcc, exec, s[26:27]
	s_cbranch_vccnz .LBB0_891
	v_lshl_add_u32 v0, s6, 6, v116
	v_cmp_gt_u32_e32 vcc, s72, v0
	v_mov_b32_e32 v69, 0
	v_mov_b32_e32 v73, 0
	v_mov_b32_e32 v72, 0
	v_mov_b32_e32 v71, 0
	v_mov_b32_e32 v70, 0
	v_mov_b32_e32 v68, 0
	v_mov_b32_e32 v67, 0
	v_mov_b32_e32 v66, 0
	s_and_saveexec_b64 s[6:7], vcc
	s_cbranch_execz .LBB0_890
	s_movk_i32 s9, 0xc00
	v_mul_lo_u32 v0, v0, s9
	v_lshl_add_u64 v[34:35], v[0:1], 1, v[96:97]
	global_load_dwordx4 v[70:73], v[34:35], off offset:3328
	global_load_dwordx4 v[66:69], v[34:35], off offset:3840

; #define LAS __attribute__((address_space(3)))
; __device__ __forceinline__ float partner32(float v, int hh) { auto rr = __builtin_amdgcn_permlane32_swap(__float_as_uint(v), __float_as_uint(v), false, false); return __uint_as_float(hh ? rr[0] : rr[1]); }
; #define MFMA32(a, b, c) __builtin_amdgcn_mfma_f32_32x32x16_bf16((a), (b), (c), 0, 0, 0)
; #define EXP2(x) __builtin_amdgcn_exp2f(x)
; __device__ __forceinline__ int crow(int i, int h) { return (i & 3) + 8 * (i >> 2) + 4 * h; }
; __device__ __forceinline__ void stick_block(const bf16x8 (&qf)[4], f32x16& o0, f32x16& o1, float& carry, LAS const unsigned char* ksb, LAS const unsigned char* vtb, int r, int hh, int tq, int key0) {
;     ...
;     for (int s = 0; s < 4; ++s) { ka[s] = *(LAS const bf16x8*)(ksb + r * KSB + (16 * s + 8 * hh) * 2); kb2[s] = *(LAS const bf16x8*)(ksb + (32 + r) * KSB + (16 * s + 8 * hh) * 2); }
;     __builtin_amdgcn_s_setprio(1);
; #pragma unroll
;     for (int s = 0; s < 4; ++s) { s0 = MFMA32(ka[s], qf[s], s0); s1 = MFMA32(kb2[s], qf[s], s1); }
;     __builtin_amdgcn_s_setprio(0);
;     __builtin_amdgcn_sched_barrier(0);
;     float acc = carry;
; #pragma unroll
;     for (int kti = 0; kti < 2; ++kti) { const int kt = 1 - kti; float spm[16], G[4], R[4];
; #pragma unroll
;         for (int i = 0; i < 16; ++i) { const float z = kt ? s1[i] : s0[i]; const bool act = key0 + 32 * kt + crow(i, hh) < tq;
;             const float sp = fmaxf(z, 0.f) + __log2f(1.f + EXP2(-fabsf(z)));
;             spm[i] = act ? sp : 0.f; const float lw = act ? z - sp : -INFINITY; if (kt) s1[i] = lw; else s0[i] = lw; }
; #pragma unroll
;         for (int g = 0; g < 4; ++g) { G[g] = (spm[4 * g] + spm[4 * g + 1]) + (spm[4 * g + 2] + spm[4 * g + 3]); R[g] = partner32(G[g], hh); }
.LBB0_891:
	s_xor_b64 s[4:5], s[4:5], -1
	s_andn2_b64 vcc, exec, s[4:5]
	s_mov_b64 s[4:5], -1
	s_cbranch_vccnz .LBB0_894
	s_add_i32 s4, s17, 0xc0
	s_cmp_gt_i32 s4, s24
	s_mov_b64 s[4:5], 0
	s_cbranch_scc1 .LBB0_894
	v_add3_u32 v0, s8, v122, v92
	ds_read_b128 v[34:37], v0
	ds_read_b128 v[98:101], v0 offset:32
	ds_read_b128 v[38:41], v0 offset:4608
	ds_read_b128 v[102:105], v0 offset:4640
	ds_read_b128 v[106:109], v0 offset:64
	ds_read_b128 v[110:113], v0 offset:96
	ds_read_b128 v[190:193], v0 offset:4672
	ds_read_b128 v[194:197], v0 offset:4704
	s_setprio 1
	s_waitcnt lgkmcnt(7)
	v_mfma_f32_32x32x16_bf16 v[50:65], v[34:37], v[74:77], 0
	s_waitcnt lgkmcnt(5)
	v_mfma_f32_32x32x16_bf16 v[34:49], v[38:41], v[74:77], 0
	v_mfma_f32_32x32x16_bf16 v[50:65], v[98:101], v[78:81], v[50:65]
	s_waitcnt lgkmcnt(4)
	v_mfma_f32_32x32x16_bf16 v[34:49], v[102:105], v[78:81], v[34:49]
	s_waitcnt lgkmcnt(3)
	v_mfma_f32_32x32x16_bf16 v[50:65], v[106:109], v[82:85], v[50:65]
	s_waitcnt lgkmcnt(1)
	v_mfma_f32_32x32x16_bf16 v[34:49], v[190:193], v[82:85], v[34:49]
	v_mfma_f32_32x32x16_bf16 v[50:65], v[110:113], v[86:89], v[50:65]
	s_waitcnt lgkmcnt(0)
	v_mfma_f32_32x32x16_bf16 v[34:49], v[194:197], v[86:89], v[34:49]
	s_setprio 0
	s_nop 10
	v_exp_f32_e64 v0, -|v34|
	v_exp_f32_e64 v99, -|v35|
	v_max_f32_e32 v98, v34, v34
	v_max_f32_e32 v98, 0, v98
	v_add_f32_e32 v0, 1.0, v0
	v_log_f32_e32 v0, v0
	v_exp_f32_e64 v103, -|v37|
	v_add_u32_e32 v94, s17, v93
	v_max_f32_e32 v102, v36, v36
	v_add_f32_e32 v171, v98, v0
	v_add_f32_e32 v0, 1.0, v99
	v_log_f32_e32 v0, v0
	v_max_f32_e32 v99, v35, v35
	v_max_f32_e32 v99, 0, v99
	v_add_u32_e32 v98, 0xe1, v94
	v_add_f32_e32 v0, v99, v0
	v_exp_f32_e64 v99, -|v36|
	v_cmp_lt_i32_e64 s[4:5], v98, v90
	v_add_u32_e32 v98, 0xe2, v94
	v_cmp_lt_i32_e64 s[42:43], v98, v90
	v_add_f32_e32 v99, 1.0, v99
	v_log_f32_e32 v99, v99
	v_add_f32_e32 v98, 1.0, v103
	v_log_f32_e32 v98, v98
	v_max_f32_e32 v102, 0, v102
	v_add_f32_e32 v165, v102, v99
	v_max_f32_e32 v102, v37, v37
	v_max_f32_e32 v102, 0, v102
	v_add_f32_e32 v167, v102, v98
	v_exp_f32_e64 v98, -|v38|
	v_exp_f32_e64 v103, -|v39|
	v_max_f32_e32 v102, v38, v38
	v_max_f32_e32 v102, 0, v102
	v_add_f32_e32 v98, 1.0, v98
	v_log_f32_e32 v98, v98
	v_exp_f32_e64 v104, -|v41|
	v_exp_f32_e64 v105, -|v45|
	v_exp_f32_e64 v107, -|v49|
	v_add_f32_e32 v169, v102, v98
	v_add_f32_e32 v98, 1.0, v103
	v_log_f32_e32 v98, v98
	v_max_f32_e32 v103, v39, v39
	v_max_f32_e32 v103, 0, v103
	v_add_u32_e32 v102, 0xe9, v94
	v_add_f32_e32 v173, v103, v98
	v_exp_f32_e64 v98, -|v40|
	v_max_f32_e32 v103, v40, v40
	v_max_f32_e32 v103, 0, v103
	v_cmp_lt_i32_e64 s[50:51], v102, v90
	v_add_f32_e32 v98, 1.0, v98
	v_log_f32_e32 v98, v98
	v_add_u32_e32 v102, 0xea, v94
	v_cmp_lt_i32_e64 s[52:53], v102, v90
	v_add_u32_e32 v102, 0xeb, v94
	v_add_f32_e32 v183, v103, v98
	v_add_f32_e32 v98, 1.0, v104
	v_log_f32_e32 v98, v98
	v_max_f32_e32 v103, v41, v41
	v_max_f32_e32 v103, 0, v103
	v_exp_f32_e64 v104, -|v43|
	v_add_f32_e32 v185, v103, v98
	v_exp_f32_e64 v98, -|v42|
	v_max_f32_e32 v103, v42, v42
	v_max_f32_e32 v103, 0, v103
	v_cmp_lt_i32_e64 s[54:55], v102, v90
	v_add_f32_e32 v98, 1.0, v98
	v_log_f32_e32 v98, v98
	v_add_u32_e32 v102, 0xf0, v94
	v_cmp_lt_i32_e64 s[56:57], v102, v90
	v_add_u32_e32 v102, 0xf1, v94
	v_add_f32_e32 v190, v103, v98
	v_add_f32_e32 v98, 1.0, v104
	v_log_f32_e32 v98, v98
	v_max_f32_e32 v103, v43, v43
	v_max_f32_e32 v103, 0, v103
	v_cmp_lt_i32_e64 s[58:59], v102, v90
	v_add_f32_e32 v191, v103, v98
	v_exp_f32_e64 v103, -|v44|
	v_add_u32_e32 v102, 0xf2, v94
	v_max_f32_e32 v104, v44, v44
	v_cmp_lt_i32_e64 s[60:61], v102, v90
	v_add_f32_e32 v103, 1.0, v103
	v_log_f32_e32 v103, v103
	v_add_f32_e32 v102, 1.0, v105
	v_exp_f32_e64 v105, -|v47|
	v_max_f32_e32 v104, 0, v104
	v_add_f32_e32 v193, v104, v103
	v_add_u32_e32 v103, 0xf3, v94
	v_cmp_lt_i32_e64 s[62:63], v103, v90
	v_add_u32_e32 v103, 0xf8, v94
	v_cmp_lt_i32_e64 s[64:65], v103, v90
	v_add_f32_e32 v103, 1.0, v105
	v_log_f32_e32 v103, v103
	v_max_f32_e32 v105, v47, v47
	v_max_f32_e32 v105, 0, v105
	v_add_u32_e32 v101, 0xe0, v94
	v_add_f32_e32 v147, v105, v103
	v_exp_f32_e64 v103, -|v48|
	v_max_f32_e32 v105, v48, v48
	v_max_f32_e32 v105, 0, v105
	v_add_u32_e32 v99, 0xe3, v94
	v_add_f32_e32 v103, 1.0, v103
	v_log_f32_e32 v103, v103
	v_cmp_lt_i32_e64 s[48:49], v101, v90
	v_cmp_lt_i32_e64 s[44:45], v99, v90
	v_cndmask_b32_e64 v177, 0, v0, s[4:5]
	v_add_f32_e32 v201, v105, v103
	v_add_f32_e32 v103, 1.0, v107
	v_log_f32_e32 v103, v103
	v_max_f32_e32 v105, v49, v49
	v_cndmask_b32_e64 v101, 0, v171, s[48:49]
	v_cndmask_b32_e64 v181, 0, v165, s[42:43]
	v_cndmask_b32_e64 v187, 0, v167, s[44:45]
	v_log_f32_e32 v102, v102
	v_max_f32_e32 v105, 0, v105
	v_add_f32_e32 v203, v105, v103
	v_add_f32_e32 v101, v101, v177
	v_add_f32_e32 v103, v181, v187
	v_add_u32_e32 v99, 0xe8, v94
	v_max_f32_e32 v104, v45, v45
	v_add_f32_e32 v110, v101, v103
	v_cmp_lt_i32_e64 s[46:47], v99, v90
	v_max_f32_e32 v104, 0, v104
	v_mov_b32_e32 v101, v110
	v_mov_b32_e32 v103, v110
	v_cndmask_b32_e64 v99, 0, v169, s[46:47]
	v_cndmask_b32_e64 v175, 0, v173, s[50:51]
	v_cndmask_b32_e64 v179, 0, v183, s[52:53]
	v_cndmask_b32_e64 v189, 0, v185, s[54:55]
	v_add_f32_e32 v140, v104, v102
	v_exp_f32_e64 v102, -|v46|
	v_permlane32_swap_b32_e32 v101, v103
	v_cndmask_b32_e64 v108, v101, v103, s[0:1]
	v_add_f32_e32 v99, v99, v175
	v_add_f32_e32 v101, v179, v189
	v_add_f32_e32 v103, v99, v101
	v_mov_b32_e32 v99, v103
	v_mov_b32_e32 v101, v103
	v_add_f32_e32 v102, 1.0, v102
	s_nop 0
	v_permlane32_swap_b32_e32 v99, v101
	v_log_f32_e32 v102, v102
	v_cndmask_b32_e64 v105, v99, v101, s[0:1]
	v_exp_f32_e64 v101, -|v50|
; __device__ __forceinline__ float partner32(float v, int hh) { auto rr = __builtin_amdgcn_permlane32_swap(__float_as_uint(v), __float_as_uint(v), false, false); return __uint_as_float(hh ? rr[0] : rr[1]); }
; #define EXP2(x) __builtin_amdgcn_exp2f(x)
; __device__ __forceinline__ int crow(int i, int h) { return (i & 3) + 8 * (i >> 2) + 4 * h; }
; __device__ __forceinline__ void stick_block(const bf16x8 (&qf)[4], f32x16& o0, f32x16& o1, float& carry, LAS const unsigned char* ksb, LAS const unsigned char* vtb, int r, int hh, int tq, int key0) {
;     ...
;     for (int kti = 0; kti < 2; ++kti) { const int kt = 1 - kti; float spm[16], G[4], R[4];
; #pragma unroll
;         for (int i = 0; i < 16; ++i) { const float z = kt ? s1[i] : s0[i]; const bool act = key0 + 32 * kt + crow(i, hh) < tq;
;             const float sp = fmaxf(z, 0.f) + __log2f(1.f + EXP2(-fabsf(z)));
;             spm[i] = act ? sp : 0.f; const float lw = act ? z - sp : -INFINITY; if (kt) s1[i] = lw; else s0[i] = lw; }
; #pragma unroll
;         for (int g = 0; g < 4; ++g) { G[g] = (spm[4 * g] + spm[4 * g + 1]) + (spm[4 * g + 2] + spm[4 * g + 3]); R[g] = partner32(G[g], hh); }
; #pragma unroll
;         for (int gi = 0; gi < 4; ++gi) { const int g = 3 - gi; float run = acc + (hh ? 0.f : R[g]);
	v_max_f32_e32 v104, v46, v46
	v_max_f32_e32 v104, 0, v104
	v_add_f32_e32 v146, v104, v102
	v_add_u32_e32 v104, 0xf9, v94
	v_add_f32_e32 v101, 1.0, v101
	v_cmp_lt_i32_e64 s[66:67], v104, v90
	v_log_f32_e32 v101, v101
	v_cndmask_b32_e64 v102, 0, v146, s[64:65]
	v_cndmask_b32_e64 v200, 0, v147, s[66:67]
	v_add_f32_e32 v107, v102, v200
	v_max_f32_e32 v102, v50, v50
	v_exp_f32_e64 v109, -|v53|
	v_max_f32_e32 v102, 0, v102
	v_add_f32_e32 v207, v102, v101
	v_add_u32_e32 v101, 0xc1, v94
	v_cmp_lt_i32_e64 s[74:75], v101, v90
	v_add_u32_e32 v101, 0xc2, v94
	v_cmp_lt_i32_e64 s[76:77], v101, v90
	v_add_f32_e32 v101, 1.0, v109
	v_log_f32_e32 v101, v101
	v_exp_f32_e64 v113, -|v55|
	v_max_f32_e32 v109, v53, v53
	v_max_f32_e32 v109, 0, v109
	v_add_f32_e32 v212, v109, v101
	v_add_u32_e32 v109, 0xc8, v94
	v_cmp_lt_i32_e64 s[86:87], v109, v90
	v_add_f32_e32 v109, 1.0, v113
	v_log_f32_e32 v109, v109
	v_max_f32_e32 v113, v55, v55
	v_max_f32_e32 v113, 0, v113
	v_exp_f32_e64 v115, -|v57|
	v_add_f32_e32 v218, v113, v109
	v_exp_f32_e64 v109, -|v56|
	v_max_f32_e32 v113, v56, v56
	v_max_f32_e32 v113, 0, v113
	v_add_u32_e32 v104, 0xfa, v94
	v_add_f32_e32 v109, 1.0, v109
	v_log_f32_e32 v109, v109
	s_mov_b64 s[18:19], s[68:69]
	v_cmp_lt_i32_e64 s[68:69], v104, v90
	v_add_u32_e32 v104, 0xfb, v94
	v_add_f32_e32 v229, v113, v109
	v_add_f32_e32 v109, 1.0, v115
	v_log_f32_e32 v109, v109
	v_max_f32_e32 v113, v57, v57
	v_max_f32_e32 v113, 0, v113
	v_exp_f32_e64 v115, -|v59|
	v_add_f32_e32 v231, v113, v109
	v_exp_f32_e64 v109, -|v58|
	v_max_f32_e32 v113, v58, v58
	v_max_f32_e32 v113, 0, v113
	s_mov_b32 s39, s38
	v_add_f32_e32 v109, 1.0, v109
	v_log_f32_e32 v109, v109
	s_mov_b32 s38, s70
	v_cmp_lt_i32_e64 s[70:71], v104, v90
	v_exp_f32_e64 v104, -|v51|
	v_add_f32_e32 v233, v113, v109
	v_add_f32_e32 v109, 1.0, v115
	v_log_f32_e32 v109, v109
	v_max_f32_e32 v113, v59, v59
	v_max_f32_e32 v113, 0, v113
	v_exp_f32_e64 v115, -|v61|
	v_add_f32_e32 v234, v113, v109
	v_exp_f32_e64 v109, -|v60|
	v_max_f32_e32 v113, v60, v60
	v_max_f32_e32 v113, 0, v113
	v_exp_f32_e64 v101, -|v54|
	v_add_f32_e32 v109, 1.0, v109
	v_log_f32_e32 v109, v109
	v_add_u32_e32 v100, 0xc0, v94
	v_cmp_lt_i32_e64 s[72:73], v100, v90
	v_add_f32_e32 v100, 1.0, v104
	v_add_f32_e32 v236, v113, v109
	v_add_f32_e32 v109, 1.0, v115
	v_log_f32_e32 v109, v109
	v_max_f32_e32 v113, v61, v61
	v_max_f32_e32 v113, 0, v113
	v_exp_f32_e64 v115, -|v63|
	v_add_f32_e32 v238, v113, v109
	v_exp_f32_e64 v109, -|v62|
	v_max_f32_e32 v113, v62, v62
	v_max_f32_e32 v113, 0, v113
	v_log_f32_e32 v100, v100
	v_add_f32_e32 v109, 1.0, v109
	v_log_f32_e32 v109, v109
	v_add_f32_e32 v101, 1.0, v101
	v_max_f32_e32 v102, v51, v51
	v_log_f32_e32 v101, v101
	v_add_f32_e32 v240, v113, v109
	v_add_f32_e32 v109, 1.0, v115
	v_log_f32_e32 v109, v109
	v_max_f32_e32 v115, v63, v63
	v_max_f32_e32 v102, 0, v102
	v_max_f32_e32 v115, 0, v115
	v_add_f32_e32 v210, v102, v100
	v_exp_f32_e64 v102, -|v52|
	v_max_f32_e32 v111, v54, v54
	v_add_f32_e32 v241, v115, v109
	v_exp_f32_e64 v115, -|v64|
	v_max_f32_e32 v111, 0, v111
	v_add_f32_e32 v213, v111, v101
	v_add_u32_e32 v111, 0xc9, v94
	v_exp_f32_e64 v196, -|v65|
	v_cmp_lt_i32_e64 s[80:81], v111, v90
	v_add_u32_e32 v111, 0xca, v94
	v_add_f32_e32 v102, 1.0, v102
	v_cmp_lt_i32_e64 s[82:83], v111, v90
	v_add_u32_e32 v111, 0xcb, v94
	v_add_u32_e32 v113, 0xd9, v94
	v_add_f32_e32 v115, 1.0, v115
	v_log_f32_e32 v102, v102
	v_cmp_lt_i32_e64 s[84:85], v111, v90
	v_add_u32_e32 v111, 0xd0, v94
	v_cmp_lt_i32_e64 s[6:7], v113, v90
	v_add_u32_e32 v113, 0xda, v94
	v_log_f32_e32 v115, v115
	v_cmp_lt_i32_e64 s[88:89], v111, v90
	v_add_u32_e32 v111, 0xd1, v94
	v_cmp_lt_i32_e64 s[8:9], v113, v90
	v_add_f32_e32 v113, 1.0, v196
	v_max_f32_e32 v104, v52, v52
	v_cmp_lt_i32_e64 s[90:91], v111, v90
	v_add_u32_e32 v111, 0xd2, v94
	v_max_f32_e32 v195, v64, v64
	v_log_f32_e32 v113, v113
	v_max_f32_e32 v104, 0, v104
	v_cmp_lt_i32_e64 s[92:93], v111, v90
	v_add_u32_e32 v111, 0xd3, v94
	v_max_f32_e32 v195, 0, v195
	v_add_f32_e32 v211, v104, v102
	v_add_u32_e32 v104, 0xc3, v94
	v_cndmask_b32_e64 v101, 0, v213, s[86:87]
	v_cndmask_b32_e64 v219, 0, v218, s[80:81]
	v_cndmask_b32_e64 v230, 0, v229, s[82:83]
	v_cndmask_b32_e64 v232, 0, v231, s[84:85]
	v_cmp_lt_i32_e64 s[94:95], v111, v90
	v_add_u32_e32 v111, 0xd8, v94
	v_add_f32_e32 v242, v195, v115
	v_add_u32_e32 v94, 0xdb, v94
	v_max_f32_e32 v115, v65, v65
	v_max_f32_e32 v115, 0, v115
	v_cmp_lt_i32_e32 vcc, v94, v90
	v_add_f32_e32 v94, v101, v219
	v_add_f32_e32 v101, v230, v232
	v_add_f32_e32 v243, v115, v113
	v_add_f32_e32 v113, v94, v101
	v_mov_b32_e32 v94, v113
	v_mov_b32_e32 v101, v113
	v_cndmask_b32_e64 v194, 0, v233, s[88:89]
	v_cndmask_b32_e64 v235, 0, v234, s[90:91]
	v_cndmask_b32_e64 v237, 0, v236, s[92:93]
	v_cndmask_b32_e64 v239, 0, v238, s[94:95]
	v_permlane32_swap_b32_e32 v94, v101
	v_cndmask_b32_e64 v101, v94, v101, s[0:1]
	v_add_f32_e32 v94, v194, v235
	v_add_f32_e32 v115, v237, v239
	v_cndmask_b32_e64 v202, 0, v201, s[68:69]
	v_cndmask_b32_e64 v204, 0, v203, s[70:71]
	v_add_f32_e32 v198, v94, v115
	v_cndmask_b32_e64 v106, 0, v190, s[56:57]
	v_cndmask_b32_e64 v98, 0, v191, s[58:59]
	v_add_f32_e32 v99, v202, v204
	v_mov_b32_e32 v94, v198
	v_mov_b32_e32 v115, v198
	s_nop 1
	v_permlane32_swap_b32_e32 v94, v115
	v_pk_add_f32 v[106:107], v[106:107], v[98:99]
	v_cndmask_b32_e64 v199, v94, v115, s[0:1]
	v_mov_b32_e32 v94, v107
	v_mov_b32_e32 v99, v107
	v_cndmask_b32_e64 v192, 0, v193, s[60:61]
	v_cndmask_b32_e64 v141, 0, v140, s[62:63]
	v_permlane32_swap_b32_e32 v94, v99
	v_add_f32_e32 v114, v192, v141
	v_cndmask_b32_e64 v115, v94, v99, s[0:1]
	v_pk_add_f32 v[106:107], v[106:107], v[114:115]
; #define LAS __attribute__((address_space(3)))
; __device__ __forceinline__ unsigned cvtpk(float lo, float hi) { f32x2_t v = {lo, hi}; bf16x2_t b = __builtin_convertvector(v, bf16x2_t); return __builtin_bit_cast(unsigned, b); }
; #define MFMA32(a, b, c) __builtin_amdgcn_mfma_f32_32x32x16_bf16((a), (b), (c), 0, 0, 0)
; #define EXP2(x) __builtin_amdgcn_exp2f(x)
; __device__ __forceinline__ void pv_accum(const f32x16& s0, const f32x16& s1, f32x16& o0, f32x16& o1, LAS const unsigned char* vtb, int r, int hh) {
;     __builtin_amdgcn_s_setprio(1);
; #pragma unroll
;     for (int kt = 0; kt < 2; ++kt)
; #pragma unroll
;         for (int sp = 0; sp < 2; ++sp) { u32x4 w;
;             if (kt == 0) { w.x = cvtpk(s0[8 * sp], s0[8 * sp + 1]); w.y = cvtpk(s0[8 * sp + 2], s0[8 * sp + 3]); w.z = cvtpk(s0[8 * sp + 4], s0[8 * sp + 5]); w.w = cvtpk(s0[8 * sp + 6], s0[8 * sp + 7]); }
;             else         { w.x = cvtpk(s1[8 * sp], s1[8 * sp + 1]); w.y = cvtpk(s1[8 * sp + 2], s1[8 * sp + 3]); w.z = cvtpk(s1[8 * sp + 4], s1[8 * sp + 5]); w.w = cvtpk(s1[8 * sp + 6], s1[8 * sp + 7]); }
;             const bf16x8 pb = __builtin_bit_cast(bf16x8, w); const int ko = 32 * kt + 16 * sp + 4 * hh;
;             { const s16x4 lo = *(LAS const s16x4*)(vtb + r * VTB + ko * 2), hi = *(LAS const s16x4*)(vtb + r * VTB + (ko + 8) * 2);
;               o0 = MFMA32(__builtin_shufflevector(lo, hi, 0, 1, 2, 3, 4, 5, 6, 7), pb, o0); }
;             { const s16x4 lo = *(LAS const s16x4*)(vtb + (32 + r) * VTB + ko * 2), hi = *(LAS const s16x4*)(vtb + (32 + r) * VTB + (ko + 8) * 2);
;               o1 = MFMA32(__builtin_shufflevector(lo, hi, 0, 1, 2, 3, 4, 5, 6, 7), pb, o1); } }
; __device__ __forceinline__ void stick_block(const bf16x8 (&qf)[4], f32x16& o0, f32x16& o1, float& carry, LAS const unsigned char* ksb, LAS const unsigned char* vtb, int r, int hh, int tq, int key0) {
;     ...
;         for (int gi = 0; gi < 4; ++gi) { const int g = 3 - gi; float run = acc + (hh ? 0.f : R[g]);
; #pragma unroll
;             for (int ki = 0; ki < 4; ++ki) { const int i = 4 * g + 3 - ki; const float lw = kt ? s1[i] : s0[i]; const float wv = EXP2(lw - run); if (kt) s1[i] = wv; else s0[i] = wv; run += spm[i]; }
;             acc += G[g] + R[g]; } }
	v_cmp_lt_i32_e64 s[96:97], v111, v90
	v_mov_b32_e32 v94, v106
	v_mov_b32_e32 v99, v106
	s_nop 1
	v_permlane32_swap_b32_e32 v94, v99
	v_cndmask_b32_e64 v94, v94, v99, s[0:1]
	v_pk_add_f32 v[106:107], v[106:107], v[94:95]
	v_cndmask_b32_e32 v244, 0, v243, vcc
	v_cndmask_b32_e64 v99, 0, v115, s[0:1]
	v_pk_add_f32 v[114:115], v[106:107], v[106:107] op_sel:[0,1] op_sel_hi:[1,0]
	v_cndmask_b32_e64 v111, 0, v240, s[96:97]
	v_cndmask_b32_e64 v109, 0, v241, s[6:7]
	v_cndmask_b32_e64 v195, 0, v242, s[8:9]
	v_add_f32_e32 v194, v103, v105
	v_mov_b32_e32 v115, v244
	v_pk_add_f32 v[196:197], v[194:195], v[114:115]
	v_pk_add_f32 v[110:111], v[110:111], v[108:109]
	v_cndmask_b32_e64 v247, 0, v94, s[0:1]
	v_pk_add_f32 v[110:111], v[110:111], v[196:197]
	v_cmp_lt_i32_e64 s[78:79], v104, v90
	v_mov_b32_e32 v94, v111
	v_mov_b32_e32 v103, v111
	s_nop 1
	v_permlane32_swap_b32_e32 v94, v103
	v_cndmask_b32_e64 v94, v94, v103, s[0:1]
	v_cndmask_b32_e64 v106, 0, v94, s[0:1]
	v_add_f32_e32 v94, v111, v94
	v_cndmask_b32_e64 v205, 0, v105, s[0:1]
	v_cndmask_b32_e64 v102, 0, v211, s[76:77]
	v_cndmask_b32_e64 v104, 0, v212, s[78:79]
	v_cndmask_b32_e64 v245, 0, v199, s[0:1]
	v_add_f32_e32 v105, v110, v94
	v_add_f32_e32 v103, v198, v199
	v_sub_f32_e32 v61, v61, v238
	v_pk_add_f32 v[198:199], v[102:103], v[104:105]
	v_sub_f32_e32 v65, v65, v243
	v_cndmask_b32_e64 v61, v215, v61, s[94:95]
	v_add_f32_e32 v105, v245, v105
	v_sub_f32_e32 v60, v60, v236
	v_cndmask_b32_e64 v246, 0, v101, s[0:1]
	v_cndmask_b32_e32 v65, v215, v65, vcc
	v_add_f32_e32 v106, v110, v106
	v_sub_f32_e32 v64, v64, v242
	v_sub_f32_e32 v61, v61, v105
	v_cndmask_b32_e64 v60, v215, v60, s[92:93]
	v_add_f32_e32 v105, v239, v105
	v_sub_f32_e32 v59, v59, v234
	v_sub_f32_e32 v57, v57, v231
	v_cndmask_b32_e64 v206, 0, v108, s[0:1]
	v_add_f32_e32 v103, v246, v199
	v_sub_f32_e32 v65, v65, v106
	v_cndmask_b32_e64 v64, v215, v64, s[8:9]
	v_add_f32_e32 v106, v244, v106
	v_sub_f32_e32 v63, v63, v241
	v_sub_f32_e32 v60, v60, v105
	v_cndmask_b32_e64 v59, v215, v59, s[90:91]
	v_add_f32_e32 v105, v237, v105
	v_sub_f32_e32 v58, v58, v233
	v_cndmask_b32_e64 v57, v215, v57, s[84:85]
	v_add_f32_e32 v108, v232, v103
	v_sub_f32_e32 v64, v64, v106
	v_cndmask_b32_e64 v63, v215, v63, s[6:7]
	v_add_f32_e32 v106, v195, v106
	v_sub_f32_e32 v62, v62, v240
	v_sub_f32_e32 v59, v59, v105
	v_cndmask_b32_e64 v58, v215, v58, s[88:89]
	v_add_f32_e32 v105, v235, v105
	v_sub_f32_e32 v57, v57, v103
	v_add_f32_e32 v103, v206, v196
	v_sub_f32_e32 v63, v63, v106
	v_cndmask_b32_e64 v62, v215, v62, s[96:97]
	v_add_f32_e32 v106, v109, v106
	v_sub_f32_e32 v58, v58, v105
	v_sub_f32_e32 v56, v56, v229
	v_add_f32_e32 v105, v187, v103
	v_sub_f32_e32 v62, v62, v106
	v_cndmask_b32_e64 v56, v215, v56, s[82:83]
	v_sub_f32_e32 v34, v34, v171
	v_add_f32_e32 v106, v181, v105
	v_add_f32_e32 v111, v230, v108
	v_sub_f32_e32 v56, v56, v108
	v_cndmask_b32_e64 v34, v215, v34, s[48:49]
	v_add_f32_e32 v108, v177, v106
	v_sub_f32_e32 v34, v34, v108
	v_exp_f32_e32 v108, v34
	v_sub_f32_e32 v34, v49, v203
	v_cndmask_b32_e64 v34, v215, v34, s[70:71]
	v_add_f32_e32 v49, v95, v99
	v_sub_f32_e32 v34, v34, v49
	v_exp_f32_e32 v99, v34
	v_sub_f32_e32 v34, v48, v201
	v_cndmask_b32_e64 v34, v215, v34, s[68:69]
	v_add_f32_e32 v48, v204, v49
	v_sub_f32_e32 v34, v34, v48
	v_exp_f32_e32 v49, v34
	v_sub_f32_e32 v34, v47, v147
	v_cndmask_b32_e64 v34, v215, v34, s[66:67]
	v_add_f32_e32 v47, v202, v48
	v_sub_f32_e32 v34, v34, v47
	v_exp_f32_e32 v48, v34
	v_sub_f32_e32 v34, v46, v146
	v_cndmask_b32_e64 v34, v215, v34, s[64:65]
	v_add_f32_e32 v46, v200, v47
	v_sub_f32_e32 v34, v34, v46
	v_exp_f32_e32 v46, v34
	v_sub_f32_e32 v34, v45, v140
	v_cndmask_b32_e64 v34, v215, v34, s[62:63]
	v_add_f32_e32 v45, v247, v107
	v_sub_f32_e32 v34, v34, v45
	v_exp_f32_e32 v47, v34
	v_sub_f32_e32 v34, v44, v193
	v_cndmask_b32_e64 v34, v215, v34, s[60:61]
	v_add_f32_e32 v44, v141, v45
	v_sub_f32_e32 v34, v34, v44
	v_exp_f32_e32 v45, v34
	v_sub_f32_e32 v34, v43, v191
	v_cndmask_b32_e64 v34, v215, v34, s[58:59]
	v_add_f32_e32 v43, v192, v44
	v_sub_f32_e32 v34, v34, v43
	v_exp_f32_e32 v44, v34
	v_sub_f32_e32 v34, v42, v190
	v_add_u32_e32 v117, s37, v123
	ds_read_b64_tr_b16 v[190:191], v117 offset:36864
	ds_read_b64_tr_b16 v[192:193], v117 offset:38400
	ds_read_b64_tr_b16 v[194:195], v117 offset:36928
	ds_read_b64_tr_b16 v[196:197], v117 offset:38464
	ds_read_b64_tr_b16 v[200:201], v117 offset:39936
	ds_read_b64_tr_b16 v[202:203], v117 offset:41472
	ds_read_b64_tr_b16 v[230:231], v117 offset:40000
	ds_read_b64_tr_b16 v[232:233], v117 offset:41536
	ds_read_b64_tr_b16 v[234:235], v117 offset:43008
; #define LAS __attribute__((address_space(3)))
; __device__ __forceinline__ unsigned cvtpk(float lo, float hi) { f32x2_t v = {lo, hi}; bf16x2_t b = __builtin_convertvector(v, bf16x2_t); return __builtin_bit_cast(unsigned, b); }
; #define MFMA32(a, b, c) __builtin_amdgcn_mfma_f32_32x32x16_bf16((a), (b), (c), 0, 0, 0)
; #define EXP2(x) __builtin_amdgcn_exp2f(x)
; __device__ __forceinline__ void pv_accum(const f32x16& s0, const f32x16& s1, f32x16& o0, f32x16& o1, LAS const unsigned char* vtb, int r, int hh) {
;     __builtin_amdgcn_s_setprio(1);
; #pragma unroll
;     for (int kt = 0; kt < 2; ++kt)
; #pragma unroll
;         for (int sp = 0; sp < 2; ++sp) { u32x4 w;
;             if (kt == 0) { w.x = cvtpk(s0[8 * sp], s0[8 * sp + 1]); w.y = cvtpk(s0[8 * sp + 2], s0[8 * sp + 3]); w.z = cvtpk(s0[8 * sp + 4], s0[8 * sp + 5]); w.w = cvtpk(s0[8 * sp + 6], s0[8 * sp + 7]); }
;             else         { w.x = cvtpk(s1[8 * sp], s1[8 * sp + 1]); w.y = cvtpk(s1[8 * sp + 2], s1[8 * sp + 3]); w.z = cvtpk(s1[8 * sp + 4], s1[8 * sp + 5]); w.w = cvtpk(s1[8 * sp + 6], s1[8 * sp + 7]); }
;             const bf16x8 pb = __builtin_bit_cast(bf16x8, w); const int ko = 32 * kt + 16 * sp + 4 * hh;
;             { const s16x4 lo = *(LAS const s16x4*)(vtb + r * VTB + ko * 2), hi = *(LAS const s16x4*)(vtb + r * VTB + (ko + 8) * 2);
;               o0 = MFMA32(__builtin_shufflevector(lo, hi, 0, 1, 2, 3, 4, 5, 6, 7), pb, o0); }
;             { const s16x4 lo = *(LAS const s16x4*)(vtb + (32 + r) * VTB + ko * 2), hi = *(LAS const s16x4*)(vtb + (32 + r) * VTB + (ko + 8) * 2);
;               o1 = MFMA32(__builtin_shufflevector(lo, hi, 0, 1, 2, 3, 4, 5, 6, 7), pb, o1); } }
;     __builtin_amdgcn_s_setprio(0);
; __device__ __forceinline__ void stick_block(const bf16x8 (&qf)[4], f32x16& o0, f32x16& o1, float& carry, LAS const unsigned char* ksb, LAS const unsigned char* vtb, int r, int hh, int tq, int key0) {
;     ...
;             for (int ki = 0; ki < 4; ++ki) { const int i = 4 * g + 3 - ki; const float lw = kt ? s1[i] : s0[i]; const float wv = EXP2(lw - run); if (kt) s1[i] = wv; else s0[i] = wv; run += spm[i]; }
;             acc += G[g] + R[g]; } }
;     carry = acc;
;     __builtin_amdgcn_sched_barrier(0);
;     pv_accum(s0, s1, o0, o1, vtb, r, hh);
	ds_read_b64_tr_b16 v[236:237], v117 offset:44544
	ds_read_b64_tr_b16 v[238:239], v117 offset:43072
	ds_read_b64_tr_b16 v[240:241], v117 offset:44608
	ds_read_b64_tr_b16 v[242:243], v117 offset:46080
	ds_read_b64_tr_b16 v[244:245], v117 offset:47616
	v_cndmask_b32_e64 v34, v215, v34, s[56:57]
	v_add_f32_e32 v42, v98, v43
	v_sub_f32_e32 v34, v34, v42
	v_exp_f32_e32 v42, v34
	v_sub_f32_e32 v34, v41, v185
	v_cndmask_b32_e64 v34, v215, v34, s[54:55]
	v_add_f32_e32 v41, v205, v114
	v_sub_f32_e32 v34, v34, v41
	v_exp_f32_e32 v43, v34
	v_sub_f32_e32 v34, v40, v183
	v_cndmask_b32_e64 v34, v215, v34, s[52:53]
	v_add_f32_e32 v40, v189, v41
	v_sub_f32_e32 v34, v34, v40
	v_exp_f32_e32 v98, v34
	v_sub_f32_e32 v34, v39, v173
	v_cndmask_b32_e64 v34, v215, v34, s[50:51]
	v_add_f32_e32 v39, v179, v40
	v_sub_f32_e32 v34, v34, v39
	v_exp_f32_e32 v107, v34
	v_sub_f32_e32 v34, v38, v169
	v_cndmask_b32_e64 v34, v215, v34, s[46:47]
	v_add_f32_e32 v38, v175, v39
	v_cndmask_b32_e64 v112, 0, v207, s[72:73]
	v_cndmask_b32_e64 v100, 0, v210, s[74:75]
	v_sub_f32_e32 v34, v34, v38
	v_pk_add_f32 v[112:113], v[112:113], v[100:101]
	v_exp_f32_e32 v109, v34
	v_sub_f32_e32 v34, v37, v167
	v_pk_add_f32 v[112:113], v[112:113], v[198:199]
	v_cndmask_b32_e64 v34, v215, v34, s[44:45]
	v_mov_b32_e32 v94, v112
	v_mov_b32_e32 v101, v112
	v_sub_f32_e32 v34, v34, v103
	s_nop 0
	v_permlane32_swap_b32_e32 v94, v101
	v_exp_f32_e32 v103, v34
	v_sub_f32_e32 v34, v36, v165
	v_cndmask_b32_e64 v94, v94, v101, s[0:1]
	v_cndmask_b32_e64 v34, v215, v34, s[42:43]
	v_cndmask_b32_e64 v101, 0, v94, s[0:1]
	v_sub_f32_e32 v53, v53, v212
	v_sub_f32_e32 v34, v34, v105
	v_sub_f32_e32 v52, v52, v211
	v_cndmask_b32_e64 v53, v215, v53, s[78:79]
	v_exp_f32_e32 v105, v34
	v_add_f32_e32 v34, v101, v113
	v_sub_f32_e32 v51, v51, v210
	v_cndmask_b32_e64 v52, v215, v52, s[76:77]
	v_sub_f32_e32 v0, v35, v0
	v_sub_f32_e32 v35, v53, v34
	v_add_f32_e32 v34, v104, v34
	v_sub_f32_e32 v50, v50, v207
	v_cndmask_b32_e64 v51, v215, v51, s[74:75]
	v_exp_f32_e32 v39, v35
	v_sub_f32_e32 v35, v52, v34
	v_add_f32_e32 v34, v102, v34
	v_cndmask_b32_e64 v50, v215, v50, s[72:73]
	v_exp_f32_e32 v40, v35
	v_sub_f32_e32 v35, v51, v34
	v_add_f32_e32 v34, v100, v34
	v_sub_f32_e32 v54, v54, v213
	v_sub_f32_e32 v55, v55, v218
	v_sub_f32_e32 v34, v50, v34
	v_cndmask_b32_e64 v54, v215, v54, s[86:87]
	v_add_f32_e32 v115, v219, v111
	v_cndmask_b32_e64 v55, v215, v55, s[80:81]
	v_cndmask_b32_e64 v0, v215, v0, s[4:5]
	v_exp_f32_e32 v41, v34
	v_add_f32_e32 v34, v112, v94
	v_sub_f32_e32 v54, v54, v115
	v_sub_f32_e32 v55, v55, v111
	s_mov_b32 s73, 0xc2ce8ed0
	s_movk_i32 s72, 0x1000
	s_brev_b32 s75, -2
	s_mov_b32 s74, 0x42b17218
	s_mov_b32 s71, 0x800000
	s_mov_b32 s70, s38
	s_mov_b32 s38, s39
	s_movk_i32 s39, 0x1800
	s_mov_b64 s[68:69], s[18:19]
	v_readlane_b32 s67, v252, 8
	v_sub_f32_e32 v0, v0, v106
	v_add_f32_e32 v95, v34, v113
	v_exp_f32_e32 v54, v54
	v_exp_f32_e32 v65, v65
	v_exp_f32_e32 v64, v64
	v_exp_f32_e32 v63, v63
	v_exp_f32_e32 v62, v62
	v_exp_f32_e32 v61, v61
	v_exp_f32_e32 v60, v60
	v_exp_f32_e32 v59, v59
	v_exp_f32_e32 v58, v58
	v_exp_f32_e32 v57, v57
	v_exp_f32_e32 v56, v56
	v_exp_f32_e32 v55, v55
	v_exp_f32_e32 v0, v0
	v_exp_f32_e32 v38, v35
	s_setprio 1
	ds_read_b64_tr_b16 v[34:35], v117 offset:46144
	ds_read_b64_tr_b16 v[36:37], v117 offset:47680
	v_cvt_pk_bf16_f32 v38, v41, v38
	v_cvt_pk_bf16_f32 v39, v40, v39
	v_cvt_pk_bf16_f32 v40, v54, v55
	v_cvt_pk_bf16_f32 v41, v56, v57
	s_waitcnt lgkmcnt(2)
	s_nop 0
	v_mfma_f32_32x32x16_bf16 v[18:33], v[190:193], v[38:41], v[18:33]
	v_mfma_f32_32x32x16_bf16 v[2:17], v[194:197], v[38:41], v[2:17]
	s_nop 0
	v_cvt_pk_bf16_f32 v38, v58, v59
	v_cvt_pk_bf16_f32 v39, v60, v61
	v_cvt_pk_bf16_f32 v40, v62, v63
	v_cvt_pk_bf16_f32 v41, v64, v65
	s_nop 1
	v_mfma_f32_32x32x16_bf16 v[18:33], v[200:203], v[38:41], v[18:33]
	v_mfma_f32_32x32x16_bf16 v[2:17], v[230:233], v[38:41], v[2:17]
	s_nop 0
	v_cvt_pk_bf16_f32 v38, v108, v0
	v_cvt_pk_bf16_f32 v39, v105, v103
	v_cvt_pk_bf16_f32 v40, v109, v107
	v_cvt_pk_bf16_f32 v41, v98, v43
	s_nop 1
	v_mfma_f32_32x32x16_bf16 v[18:33], v[234:237], v[38:41], v[18:33]
	v_mfma_f32_32x32x16_bf16 v[2:17], v[238:241], v[38:41], v[2:17]
	s_nop 0
	v_cvt_pk_bf16_f32 v38, v42, v44
	v_cvt_pk_bf16_f32 v39, v45, v47
	v_cvt_pk_bf16_f32 v40, v46, v48
	v_cvt_pk_bf16_f32 v41, v49, v99
	s_waitcnt lgkmcnt(0)
	s_nop 0
	v_mfma_f32_32x32x16_bf16 v[18:33], v[242:245], v[38:41], v[18:33]
	v_mfma_f32_32x32x16_bf16 v[2:17], v[34:37], v[38:41], v[2:17]
	s_setprio 0
	s_mov_b32 s4, 0x4316199a
	v_cmp_lt_f32_e32 vcc, s4, v95
	s_cmp_eq_u64 vcc, exec
	s_cselect_b64 s[4:5], -1, 0
